# GEMM K-loops: merged lgkmcnt waits (3 groups) + dead scalar bookkeeping of the now-unconditional stage writes removed from the loop bodies
# baseline (speedup 1.0000x reference)
.Lnodef_B0_0:
	ds_read_b128 v[150:153], v255 offset:12288
	ds_read_b128 v[146:149], v253 offset:8192
	ds_read_b128 v[142:145], v255 offset:8192
	ds_read_b128 v[154:157], v253 offset:12288
	s_waitcnt lgkmcnt(4)
	v_mfma_f32_16x16x32_bf16 v[122:125], v[158:161], v[126:129], v[122:125]
	v_mfma_f32_16x16x32_bf16 v[118:121], v[162:165], v[126:129], v[118:121]
	v_mfma_f32_16x16x32_bf16 v[114:117], v[166:169], v[126:129], v[114:117]
	ds_read_b128 v[126:129], v247
	s_waitcnt lgkmcnt(2)
	v_mfma_f32_16x16x32_bf16 v[110:113], v[158:161], v[130:133], v[110:113]
	v_mfma_f32_16x16x32_bf16 v[106:109], v[162:165], v[130:133], v[106:109]
	v_mfma_f32_16x16x32_bf16 v[102:105], v[166:169], v[130:133], v[102:105]
	s_waitcnt vmcnt(5)
	ds_write_b128 v238, v[26:29]
	ds_write_b128 v238, v[22:25] offset:8192
.LBB0_287:
	s_lshl_b32 s2, s44, 8
	s_ashr_i32 s3, s2, 31
	s_lshl_b64 s[4:5], s[2:3], 11
	s_lshl_b32 s2, s22, 6
	s_ashr_i32 s3, s2, 31
	s_add_u32 s20, s25, s4
	s_addc_u32 s21, s26, s5
	s_lshl_b64 s[12:13], s[2:3], 1
	s_add_u32 s20, s20, s12
	s_addc_u32 s21, s21, s13
	global_load_dwordx4 v[22:25], v237, s[20:21]
	global_load_dwordx4 v[26:29], v236, s[20:21]
	ds_read_b128 v[130:133], v245
	v_mfma_f32_16x16x32_bf16 v[98:101], v[158:161], v[134:137], v[98:101]
	v_mfma_f32_16x16x32_bf16 v[94:97], v[162:165], v[134:137], v[94:97]
	v_mfma_f32_16x16x32_bf16 v[90:93], v[166:169], v[134:137], v[90:93]
	ds_read_b128 v[134:137], v247 offset:4096
	v_mfma_f32_16x16x32_bf16 v[86:89], v[158:161], v[138:141], v[86:89]
	v_mfma_f32_16x16x32_bf16 v[82:85], v[162:165], v[138:141], v[82:85]
	v_mfma_f32_16x16x32_bf16 v[54:57], v[166:169], v[138:141], v[54:57]
	ds_read_b128 v[170:173], v243
	ds_read_b128 v[174:177], v241
	ds_read_b128 v[178:181], v243 offset:4096
	ds_read_b128 v[138:141], v245 offset:4096
	s_waitcnt lgkmcnt(9)
	v_mfma_f32_16x16x32_bf16 v[78:81], v[158:161], v[142:145], v[78:81]
	v_mfma_f32_16x16x32_bf16 v[74:77], v[162:165], v[142:145], v[74:77]
	v_mfma_f32_16x16x32_bf16 v[70:73], v[166:169], v[142:145], v[70:73]
	s_waitcnt vmcnt(5)
	ds_write_b128 v238, v[18:21] offset:16384
	ds_write_b128 v238, v[14:17] offset:24576
.LBB0_289:
	global_load_dwordx4 v[14:17], v235, s[20:21]
	global_load_dwordx4 v[18:21], v234, s[20:21]
	ds_read_b128 v[142:145], v247 offset:8192
	s_waitcnt lgkmcnt(4)
	v_mfma_f32_16x16x32_bf16 v[66:69], v[158:161], v[146:149], v[66:69]
	v_mfma_f32_16x16x32_bf16 v[62:65], v[162:165], v[146:149], v[62:65]
	v_mfma_f32_16x16x32_bf16 v[58:61], v[166:169], v[146:149], v[58:61]
	ds_read_b128 v[146:149], v245 offset:8192
	v_mfma_f32_16x16x32_bf16 v[50:53], v[158:161], v[150:153], v[50:53]
	v_mfma_f32_16x16x32_bf16 v[46:49], v[162:165], v[150:153], v[46:49]
	v_mfma_f32_16x16x32_bf16 v[42:45], v[166:169], v[150:153], v[42:45]
	s_waitcnt vmcnt(5)
	ds_write_b128 v238, v[10:13] offset:32768
	ds_write_b128 v238, v[6:9] offset:40960
.LBB0_291:
	s_mul_i32 s14, s43, 0xc0
	s_ashr_i32 s15, s14, 31
	s_lshl_b64 s[14:15], s[14:15], 11
	s_add_u32 s20, s27, s14
	s_addc_u32 s21, s28, s15
	s_add_u32 s12, s20, s12
	s_addc_u32 s13, s21, s13
	global_load_dwordx4 v[6:9], v237, s[12:13]
	global_load_dwordx4 v[10:13], v236, s[12:13]
	ds_read_b128 v[150:153], v247 offset:12288
	v_mfma_f32_16x16x32_bf16 v[38:41], v[158:161], v[154:157], v[38:41]
	v_mfma_f32_16x16x32_bf16 v[34:37], v[162:165], v[154:157], v[34:37]
	v_mfma_f32_16x16x32_bf16 v[30:33], v[166:169], v[154:157], v[30:33]
	ds_read_b128 v[154:157], v245 offset:12288
	s_waitcnt lgkmcnt(8)
	v_mfma_f32_16x16x32_bf16 v[122:125], v[170:173], v[126:129], v[122:125]
	v_mfma_f32_16x16x32_bf16 v[118:121], v[174:177], v[126:129], v[118:121]
	v_mfma_f32_16x16x32_bf16 v[114:117], v[178:181], v[126:129], v[114:117]
	v_mfma_f32_16x16x32_bf16 v[110:113], v[170:173], v[130:133], v[110:113]
	v_mfma_f32_16x16x32_bf16 v[106:109], v[174:177], v[130:133], v[106:109]
	v_mfma_f32_16x16x32_bf16 v[102:105], v[178:181], v[130:133], v[102:105]
	s_waitcnt vmcnt(6)
	ds_write_b128 v238, v[2:5] offset:49152

.LBB0_297:
	s_waitcnt lgkmcnt(0)
	s_barrier
	ds_read_b128 v[158:161], v250
	ds_read_b128 v[162:165], v248
	ds_read_b128 v[166:169], v250 offset:4096
	ds_read_b128 v[126:129], v254
	ds_read_b128 v[130:133], v252
	ds_read_b128 v[134:137], v254 offset:4096
	ds_read_b128 v[138:141], v252 offset:4096
	v_mfma_f32_16x16x32_bf16 v[78:81], v[170:173], v[142:145], v[78:81]
	v_mfma_f32_16x16x32_bf16 v[74:77], v[174:177], v[142:145], v[74:77]
	v_mfma_f32_16x16x32_bf16 v[70:73], v[178:181], v[142:145], v[70:73]
	v_mfma_f32_16x16x32_bf16 v[66:69], v[170:173], v[146:149], v[66:69]
	v_mfma_f32_16x16x32_bf16 v[62:65], v[174:177], v[146:149], v[62:65]
	v_mfma_f32_16x16x32_bf16 v[58:61], v[178:181], v[146:149], v[58:61]
	v_mfma_f32_16x16x32_bf16 v[50:53], v[170:173], v[150:153], v[50:53]
	v_mfma_f32_16x16x32_bf16 v[46:49], v[174:177], v[150:153], v[46:49]
	v_mfma_f32_16x16x32_bf16 v[42:45], v[178:181], v[150:153], v[42:45]
	v_mfma_f32_16x16x32_bf16 v[38:41], v[170:173], v[154:157], v[38:41]
	v_mfma_f32_16x16x32_bf16 v[34:37], v[174:177], v[154:157], v[34:37]
	v_mfma_f32_16x16x32_bf16 v[30:33], v[178:181], v[154:157], v[30:33]
	ds_read_b128 v[150:153], v254 offset:12288
	ds_read_b128 v[146:149], v252 offset:8192
	ds_read_b128 v[142:145], v254 offset:8192
	ds_read_b128 v[154:157], v252 offset:12288
	s_cmp_lt_i32 s35, s30
	s_cselect_b64 s[20:21], -1, 0
	s_cmp_ge_i32 s35, s30
	s_cselect_b64 s[12:13], -1, 0
	s_waitcnt lgkmcnt(4)
	v_mfma_f32_16x16x32_bf16 v[122:125], v[158:161], v[126:129], v[122:125]
	v_mfma_f32_16x16x32_bf16 v[118:121], v[162:165], v[126:129], v[118:121]
	v_mfma_f32_16x16x32_bf16 v[114:117], v[166:169], v[126:129], v[114:117]
	ds_read_b128 v[126:129], v246
	s_waitcnt lgkmcnt(2)
	v_mfma_f32_16x16x32_bf16 v[110:113], v[158:161], v[130:133], v[110:113]
	v_mfma_f32_16x16x32_bf16 v[106:109], v[162:165], v[130:133], v[106:109]
	v_mfma_f32_16x16x32_bf16 v[102:105], v[166:169], v[130:133], v[102:105]
	s_waitcnt vmcnt(5)
	ds_write_b128 v239, v[22:25]
	ds_write_b128 v239, v[26:29] offset:8192
.LBB0_299:
	s_lshl_b32 s2, s46, 6
	s_ashr_i32 s3, s2, 31
	s_add_u32 s22, s25, s4
	s_addc_u32 s23, s26, s5
	s_lshl_b64 s[4:5], s[2:3], 1
	s_add_u32 s22, s22, s4
	s_addc_u32 s23, s23, s5
	global_load_dwordx4 v[26:29], v237, s[22:23]
	global_load_dwordx4 v[22:25], v236, s[22:23]
	ds_read_b128 v[130:133], v244
	v_mfma_f32_16x16x32_bf16 v[98:101], v[158:161], v[134:137], v[98:101]
	v_mfma_f32_16x16x32_bf16 v[94:97], v[162:165], v[134:137], v[94:97]
	v_mfma_f32_16x16x32_bf16 v[90:93], v[166:169], v[134:137], v[90:93]
	ds_read_b128 v[134:137], v246 offset:4096
	v_mfma_f32_16x16x32_bf16 v[86:89], v[158:161], v[138:141], v[86:89]
	v_mfma_f32_16x16x32_bf16 v[82:85], v[162:165], v[138:141], v[82:85]
	v_mfma_f32_16x16x32_bf16 v[54:57], v[166:169], v[138:141], v[54:57]
	ds_read_b128 v[170:173], v242
	ds_read_b128 v[174:177], v240
	ds_read_b128 v[178:181], v242 offset:4096
	ds_read_b128 v[138:141], v244 offset:4096
	s_waitcnt lgkmcnt(9)
	v_mfma_f32_16x16x32_bf16 v[78:81], v[158:161], v[142:145], v[78:81]
	v_mfma_f32_16x16x32_bf16 v[74:77], v[162:165], v[142:145], v[74:77]
	v_mfma_f32_16x16x32_bf16 v[70:73], v[166:169], v[142:145], v[70:73]
	s_waitcnt vmcnt(5)
	ds_write_b128 v239, v[14:17] offset:16384
	ds_write_b128 v239, v[18:21] offset:24576
.LBB0_301:
	global_load_dwordx4 v[18:21], v235, s[22:23]
	global_load_dwordx4 v[14:17], v234, s[22:23]
	ds_read_b128 v[142:145], v246 offset:8192
	s_waitcnt lgkmcnt(4)
	v_mfma_f32_16x16x32_bf16 v[66:69], v[158:161], v[146:149], v[66:69]
	v_mfma_f32_16x16x32_bf16 v[62:65], v[162:165], v[146:149], v[62:65]
	v_mfma_f32_16x16x32_bf16 v[58:61], v[166:169], v[146:149], v[58:61]
	ds_read_b128 v[146:149], v244 offset:8192
	v_mfma_f32_16x16x32_bf16 v[50:53], v[158:161], v[150:153], v[50:53]
	v_mfma_f32_16x16x32_bf16 v[46:49], v[162:165], v[150:153], v[46:49]
	v_mfma_f32_16x16x32_bf16 v[42:45], v[166:169], v[150:153], v[42:45]
	s_waitcnt vmcnt(5)
	ds_write_b128 v239, v[6:9] offset:32768
	ds_write_b128 v239, v[10:13] offset:40960

.Lnodef_G0_1:
	ds_read_b128 v[186:189], v255 offset:12288
	ds_read_b128 v[182:185], v253 offset:8192
	ds_read_b128 v[178:181], v255 offset:8192
	ds_read_b128 v[190:193], v253 offset:12288
	s_waitcnt lgkmcnt(4)
	v_mfma_f32_16x16x32_bf16 v[158:161], v[194:197], v[162:165], v[158:161]
	v_mfma_f32_16x16x32_bf16 v[154:157], v[198:201], v[162:165], v[154:157]
	v_mfma_f32_16x16x32_bf16 v[150:153], v[202:205], v[162:165], v[150:153]
	v_mfma_f32_16x16x32_bf16 v[146:149], v[206:209], v[162:165], v[146:149]
	ds_read_b128 v[162:165], v247
	s_waitcnt lgkmcnt(2)
	v_mfma_f32_16x16x32_bf16 v[142:145], v[194:197], v[166:169], v[142:145]
	v_mfma_f32_16x16x32_bf16 v[138:141], v[198:201], v[166:169], v[138:141]
	v_mfma_f32_16x16x32_bf16 v[134:137], v[202:205], v[166:169], v[134:137]
	v_mfma_f32_16x16x32_bf16 v[130:133], v[206:209], v[166:169], v[130:133]
	s_waitcnt vmcnt(6)
	ds_write_b128 v235, v[30:33]
	ds_write_b128 v235, v[26:29] offset:8192
.LBB0_962:
	s_lshl_b32 s6, s51, 8
	s_ashr_i32 s7, s6, 31
	s_lshl_b32 s2, s28, 6
	s_ashr_i32 s3, s2, 31
	s_lshl_b64 s[22:23], s[6:7], 11
	s_add_u32 s26, s31, s22
	s_addc_u32 s27, s33, s23
	s_lshl_b64 s[22:23], s[2:3], 1
	s_add_u32 s26, s26, s22
	s_addc_u32 s27, s27, s23
	global_load_dwordx4 v[30:33], v233, s[26:27]
	global_load_dwordx4 v[26:29], v234, s[26:27]
	ds_read_b128 v[166:169], v245
	v_mfma_f32_16x16x32_bf16 v[126:129], v[194:197], v[170:173], v[126:129]
	v_mfma_f32_16x16x32_bf16 v[122:125], v[198:201], v[170:173], v[122:125]
	v_mfma_f32_16x16x32_bf16 v[118:121], v[202:205], v[170:173], v[118:121]
	v_mfma_f32_16x16x32_bf16 v[114:117], v[206:209], v[170:173], v[114:117]
	ds_read_b128 v[170:173], v247 offset:4096
	v_mfma_f32_16x16x32_bf16 v[110:113], v[194:197], v[174:177], v[110:113]
	v_mfma_f32_16x16x32_bf16 v[106:109], v[198:201], v[174:177], v[106:109]
	v_mfma_f32_16x16x32_bf16 v[102:105], v[202:205], v[174:177], v[102:105]
	v_mfma_f32_16x16x32_bf16 v[82:85], v[206:209], v[174:177], v[82:85]
	ds_read_b128 v[210:213], v243
	ds_read_b128 v[214:217], v241
	ds_read_b128 v[218:221], v243 offset:4096
	ds_read_b128 v[222:225], v241 offset:4096
	ds_read_b128 v[174:177], v245 offset:4096
	s_waitcnt lgkmcnt(10)
	v_mfma_f32_16x16x32_bf16 v[98:101], v[194:197], v[178:181], v[98:101]
	v_mfma_f32_16x16x32_bf16 v[94:97], v[198:201], v[178:181], v[94:97]
	v_mfma_f32_16x16x32_bf16 v[90:93], v[202:205], v[178:181], v[90:93]
	v_mfma_f32_16x16x32_bf16 v[86:89], v[206:209], v[178:181], v[86:89]
	s_waitcnt vmcnt(6)
	ds_write_b128 v235, v[22:25] offset:16384
	ds_write_b128 v235, v[18:21] offset:24576
.LBB0_964:
	global_load_dwordx4 v[18:21], v232, s[26:27]
	global_load_dwordx4 v[22:25], v231, s[26:27]
	ds_read_b128 v[178:181], v247 offset:8192
	s_waitcnt lgkmcnt(4)
	v_mfma_f32_16x16x32_bf16 v[78:81], v[194:197], v[182:185], v[78:81]
	v_mfma_f32_16x16x32_bf16 v[74:77], v[198:201], v[182:185], v[74:77]
	v_mfma_f32_16x16x32_bf16 v[70:73], v[202:205], v[182:185], v[70:73]
	v_mfma_f32_16x16x32_bf16 v[66:69], v[206:209], v[182:185], v[66:69]
	ds_read_b128 v[182:185], v245 offset:8192
	v_mfma_f32_16x16x32_bf16 v[62:65], v[194:197], v[186:189], v[62:65]
	v_mfma_f32_16x16x32_bf16 v[58:61], v[198:201], v[186:189], v[58:61]
	v_mfma_f32_16x16x32_bf16 v[54:57], v[202:205], v[186:189], v[54:57]
	v_mfma_f32_16x16x32_bf16 v[50:53], v[206:209], v[186:189], v[50:53]
	s_waitcnt vmcnt(6)
	ds_write_b128 v235, v[14:17] offset:32768
	ds_write_b128 v235, v[10:13] offset:40960
.LBB0_966:
	s_lshl_b32 s24, s50, 8
	s_ashr_i32 s25, s24, 31
	s_lshl_b64 s[26:27], s[24:25], 11
	s_add_u32 s26, s34, s26
	s_addc_u32 s27, s35, s27
	s_add_u32 s22, s26, s22
	s_addc_u32 s23, s27, s23
	global_load_dwordx4 v[10:13], v234, s[22:23]
	global_load_dwordx4 v[14:17], v233, s[22:23]
	ds_read_b128 v[186:189], v247 offset:12288
	v_mfma_f32_16x16x32_bf16 v[46:49], v[194:197], v[190:193], v[46:49]
	v_mfma_f32_16x16x32_bf16 v[42:45], v[198:201], v[190:193], v[42:45]
	v_mfma_f32_16x16x32_bf16 v[38:41], v[202:205], v[190:193], v[38:41]
	v_mfma_f32_16x16x32_bf16 v[34:37], v[206:209], v[190:193], v[34:37]
	ds_read_b128 v[190:193], v245 offset:12288
	s_waitcnt lgkmcnt(8)
	v_mfma_f32_16x16x32_bf16 v[158:161], v[210:213], v[162:165], v[158:161]
	v_mfma_f32_16x16x32_bf16 v[154:157], v[214:217], v[162:165], v[154:157]
	v_mfma_f32_16x16x32_bf16 v[150:153], v[218:221], v[162:165], v[150:153]
	v_mfma_f32_16x16x32_bf16 v[146:149], v[222:225], v[162:165], v[146:149]
	v_mfma_f32_16x16x32_bf16 v[142:145], v[210:213], v[166:169], v[142:145]
	v_mfma_f32_16x16x32_bf16 v[138:141], v[214:217], v[166:169], v[138:141]
	v_mfma_f32_16x16x32_bf16 v[134:137], v[218:221], v[166:169], v[134:137]
	v_mfma_f32_16x16x32_bf16 v[130:133], v[222:225], v[166:169], v[130:133]
	s_waitcnt vmcnt(6)
	ds_write_b128 v235, v[6:9] offset:49152
	ds_write_b128 v235, v[2:5] offset:57344

.LBB0_972:
	s_waitcnt lgkmcnt(0)
	s_barrier
	ds_read_b128 v[194:197], v250
	ds_read_b128 v[198:201], v248
	ds_read_b128 v[202:205], v250 offset:4096
	ds_read_b128 v[206:209], v248 offset:4096
	ds_read_b128 v[162:165], v254
	ds_read_b128 v[166:169], v252
	ds_read_b128 v[170:173], v254 offset:4096
	ds_read_b128 v[174:177], v252 offset:4096
	v_mfma_f32_16x16x32_bf16 v[98:101], v[210:213], v[178:181], v[98:101]
	v_mfma_f32_16x16x32_bf16 v[94:97], v[214:217], v[178:181], v[94:97]
	v_mfma_f32_16x16x32_bf16 v[90:93], v[218:221], v[178:181], v[90:93]
	v_mfma_f32_16x16x32_bf16 v[86:89], v[222:225], v[178:181], v[86:89]
	v_mfma_f32_16x16x32_bf16 v[78:81], v[210:213], v[182:185], v[78:81]
	v_mfma_f32_16x16x32_bf16 v[74:77], v[214:217], v[182:185], v[74:77]
	v_mfma_f32_16x16x32_bf16 v[70:73], v[218:221], v[182:185], v[70:73]
	v_mfma_f32_16x16x32_bf16 v[66:69], v[222:225], v[182:185], v[66:69]
	v_mfma_f32_16x16x32_bf16 v[62:65], v[210:213], v[186:189], v[62:65]
	v_mfma_f32_16x16x32_bf16 v[58:61], v[214:217], v[186:189], v[58:61]
	v_mfma_f32_16x16x32_bf16 v[54:57], v[218:221], v[186:189], v[54:57]
	v_mfma_f32_16x16x32_bf16 v[50:53], v[222:225], v[186:189], v[50:53]
	v_mfma_f32_16x16x32_bf16 v[46:49], v[210:213], v[190:193], v[46:49]
	v_mfma_f32_16x16x32_bf16 v[42:45], v[214:217], v[190:193], v[42:45]
	v_mfma_f32_16x16x32_bf16 v[38:41], v[218:221], v[190:193], v[38:41]
	v_mfma_f32_16x16x32_bf16 v[34:37], v[222:225], v[190:193], v[34:37]
	ds_read_b128 v[186:189], v254 offset:12288
	ds_read_b128 v[182:185], v252 offset:8192
	ds_read_b128 v[178:181], v254 offset:8192
	ds_read_b128 v[190:193], v252 offset:12288
	s_cmp_lt_i32 s42, s37
	s_cselect_b64 s[26:27], -1, 0
	s_cmp_ge_i32 s42, s37
	s_cselect_b64 s[6:7], -1, 0
	s_waitcnt lgkmcnt(4)
	v_mfma_f32_16x16x32_bf16 v[158:161], v[194:197], v[162:165], v[158:161]
	v_mfma_f32_16x16x32_bf16 v[154:157], v[198:201], v[162:165], v[154:157]
	v_mfma_f32_16x16x32_bf16 v[150:153], v[202:205], v[162:165], v[150:153]
	v_mfma_f32_16x16x32_bf16 v[146:149], v[206:209], v[162:165], v[146:149]
	ds_read_b128 v[162:165], v246
	s_waitcnt lgkmcnt(2)
	v_mfma_f32_16x16x32_bf16 v[142:145], v[194:197], v[166:169], v[142:145]
	v_mfma_f32_16x16x32_bf16 v[138:141], v[198:201], v[166:169], v[138:141]
	v_mfma_f32_16x16x32_bf16 v[134:137], v[202:205], v[166:169], v[134:137]
	v_mfma_f32_16x16x32_bf16 v[130:133], v[206:209], v[166:169], v[130:133]
	s_waitcnt vmcnt(6)
	ds_write_b128 v236, v[26:29]
	ds_write_b128 v236, v[30:33] offset:8192
.LBB0_974:
	s_lshl_b32 s24, s53, 6
	s_ashr_i32 s25, s24, 31
	s_lshl_b64 s[2:3], s[2:3], 1
	s_add_u32 s2, s31, s2
	s_addc_u32 s3, s33, s3
	s_lshl_b64 s[24:25], s[24:25], 1
	s_add_u32 s28, s2, s24
	s_addc_u32 s29, s3, s25
	global_load_dwordx4 v[30:33], v234, s[28:29]
	global_load_dwordx4 v[26:29], v233, s[28:29]
	ds_read_b128 v[166:169], v244
	v_mfma_f32_16x16x32_bf16 v[126:129], v[194:197], v[170:173], v[126:129]
	v_mfma_f32_16x16x32_bf16 v[122:125], v[198:201], v[170:173], v[122:125]
	v_mfma_f32_16x16x32_bf16 v[118:121], v[202:205], v[170:173], v[118:121]
	v_mfma_f32_16x16x32_bf16 v[114:117], v[206:209], v[170:173], v[114:117]
	ds_read_b128 v[170:173], v246 offset:4096
	v_mfma_f32_16x16x32_bf16 v[110:113], v[194:197], v[174:177], v[110:113]
	v_mfma_f32_16x16x32_bf16 v[106:109], v[198:201], v[174:177], v[106:109]
	v_mfma_f32_16x16x32_bf16 v[102:105], v[202:205], v[174:177], v[102:105]
	v_mfma_f32_16x16x32_bf16 v[82:85], v[206:209], v[174:177], v[82:85]
	ds_read_b128 v[210:213], v242
	ds_read_b128 v[214:217], v237
	ds_read_b128 v[218:221], v242 offset:4096
	ds_read_b128 v[222:225], v237 offset:4096
	ds_read_b128 v[174:177], v244 offset:4096
	s_waitcnt lgkmcnt(10)
	v_mfma_f32_16x16x32_bf16 v[98:101], v[194:197], v[178:181], v[98:101]
	v_mfma_f32_16x16x32_bf16 v[94:97], v[198:201], v[178:181], v[94:97]
	v_mfma_f32_16x16x32_bf16 v[90:93], v[202:205], v[178:181], v[90:93]
	v_mfma_f32_16x16x32_bf16 v[86:89], v[206:209], v[178:181], v[86:89]
	s_waitcnt vmcnt(6)
	ds_write_b128 v236, v[18:21] offset:16384
	ds_write_b128 v236, v[22:25] offset:24576
.LBB0_976:
	global_load_dwordx4 v[22:25], v232, s[28:29]
	global_load_dwordx4 v[18:21], v231, s[28:29]
	ds_read_b128 v[178:181], v246 offset:8192
	s_waitcnt lgkmcnt(4)
	v_mfma_f32_16x16x32_bf16 v[78:81], v[194:197], v[182:185], v[78:81]
	v_mfma_f32_16x16x32_bf16 v[74:77], v[198:201], v[182:185], v[74:77]
	v_mfma_f32_16x16x32_bf16 v[70:73], v[202:205], v[182:185], v[70:73]
	v_mfma_f32_16x16x32_bf16 v[66:69], v[206:209], v[182:185], v[66:69]
	ds_read_b128 v[182:185], v244 offset:8192
	v_mfma_f32_16x16x32_bf16 v[62:65], v[194:197], v[186:189], v[62:65]
	v_mfma_f32_16x16x32_bf16 v[58:61], v[198:201], v[186:189], v[58:61]
	v_mfma_f32_16x16x32_bf16 v[54:57], v[202:205], v[186:189], v[54:57]
	v_mfma_f32_16x16x32_bf16 v[50:53], v[206:209], v[186:189], v[50:53]
	s_waitcnt vmcnt(6)
	ds_write_b128 v236, v[10:13] offset:32768
	ds_write_b128 v236, v[14:17] offset:40960

.Lnodef_I0_2:
	ds_read_b128 v[186:189], v255 offset:12288
	ds_read_b128 v[182:185], v253 offset:8192
	ds_read_b128 v[178:181], v255 offset:8192
	ds_read_b128 v[190:193], v253 offset:12288
	s_waitcnt lgkmcnt(4)
	v_mfma_f32_16x16x32_bf16 v[158:161], v[194:197], v[162:165], v[158:161]
	v_mfma_f32_16x16x32_bf16 v[150:153], v[198:201], v[162:165], v[150:153]
	v_mfma_f32_16x16x32_bf16 v[154:157], v[202:205], v[162:165], v[154:157]
	v_mfma_f32_16x16x32_bf16 v[146:149], v[206:209], v[162:165], v[146:149]
	ds_read_b128 v[162:165], v247
	s_waitcnt lgkmcnt(2)
	v_mfma_f32_16x16x32_bf16 v[142:145], v[194:197], v[166:169], v[142:145]
	v_mfma_f32_16x16x32_bf16 v[134:137], v[198:201], v[166:169], v[134:137]
	v_mfma_f32_16x16x32_bf16 v[138:141], v[202:205], v[166:169], v[138:141]
	v_mfma_f32_16x16x32_bf16 v[130:133], v[206:209], v[166:169], v[130:133]
	s_waitcnt vmcnt(6)
	ds_write_b128 v235, v[30:33]
	ds_write_b128 v235, v[26:29] offset:8192
.LBB0_1150:
	s_lshl_b32 s2, s48, 8
	s_ashr_i32 s3, s2, 31
	s_lshl_b64 s[12:13], s[2:3], 11
	s_lshl_b32 s2, s22, 6
	s_ashr_i32 s3, s2, 31
	s_add_u32 s20, s11, s12
	s_addc_u32 s21, s24, s13
	s_lshl_b64 s[8:9], s[2:3], 1
	s_add_u32 s20, s20, s8
	s_addc_u32 s21, s21, s9
	global_load_dwordx4 v[30:33], v233, s[20:21]
	global_load_dwordx4 v[26:29], v234, s[20:21]
	ds_read_b128 v[166:169], v245
	v_mfma_f32_16x16x32_bf16 v[126:129], v[194:197], v[170:173], v[126:129]
	v_mfma_f32_16x16x32_bf16 v[118:121], v[198:201], v[170:173], v[118:121]
	v_mfma_f32_16x16x32_bf16 v[122:125], v[202:205], v[170:173], v[122:125]
	v_mfma_f32_16x16x32_bf16 v[114:117], v[206:209], v[170:173], v[114:117]
	ds_read_b128 v[170:173], v247 offset:4096
	v_mfma_f32_16x16x32_bf16 v[110:113], v[194:197], v[174:177], v[110:113]
	v_mfma_f32_16x16x32_bf16 v[102:105], v[198:201], v[174:177], v[102:105]
	v_mfma_f32_16x16x32_bf16 v[106:109], v[202:205], v[174:177], v[106:109]
	v_mfma_f32_16x16x32_bf16 v[66:69], v[206:209], v[174:177], v[66:69]
	ds_read_b128 v[210:213], v243
	ds_read_b128 v[214:217], v241
	ds_read_b128 v[218:221], v243 offset:4096
	ds_read_b128 v[222:225], v241 offset:4096
	ds_read_b128 v[174:177], v245 offset:4096
	s_waitcnt lgkmcnt(10)
	v_mfma_f32_16x16x32_bf16 v[98:101], v[194:197], v[178:181], v[98:101]
	v_mfma_f32_16x16x32_bf16 v[90:93], v[198:201], v[178:181], v[90:93]
	v_mfma_f32_16x16x32_bf16 v[94:97], v[202:205], v[178:181], v[94:97]
	v_mfma_f32_16x16x32_bf16 v[86:89], v[206:209], v[178:181], v[86:89]
	s_waitcnt vmcnt(6)
	ds_write_b128 v235, v[22:25] offset:16384
	ds_write_b128 v235, v[18:21] offset:24576
.LBB0_1152:
	global_load_dwordx4 v[18:21], v232, s[20:21]
	global_load_dwordx4 v[22:25], v231, s[20:21]
	ds_read_b128 v[178:181], v247 offset:8192
	s_waitcnt lgkmcnt(4)
	v_mfma_f32_16x16x32_bf16 v[82:85], v[194:197], v[182:185], v[82:85]
	v_mfma_f32_16x16x32_bf16 v[74:77], v[198:201], v[182:185], v[74:77]
	v_mfma_f32_16x16x32_bf16 v[78:81], v[202:205], v[182:185], v[78:81]
	v_mfma_f32_16x16x32_bf16 v[70:73], v[206:209], v[182:185], v[70:73]
	ds_read_b128 v[182:185], v245 offset:8192
	v_mfma_f32_16x16x32_bf16 v[62:65], v[194:197], v[186:189], v[62:65]
	v_mfma_f32_16x16x32_bf16 v[54:57], v[198:201], v[186:189], v[54:57]
	v_mfma_f32_16x16x32_bf16 v[58:61], v[202:205], v[186:189], v[58:61]
	v_mfma_f32_16x16x32_bf16 v[50:53], v[206:209], v[186:189], v[50:53]
	s_waitcnt vmcnt(6)
	ds_write_b128 v235, v[14:17] offset:32768
	ds_write_b128 v235, v[10:13] offset:40960
.LBB0_1154:
	s_lshl_b32 s14, s47, 8
	s_ashr_i32 s15, s14, 31
	s_lshl_b64 s[14:15], s[14:15], 11
	s_add_u32 s20, s25, s14
	s_addc_u32 s21, s26, s15
	s_add_u32 s8, s20, s8
	s_addc_u32 s9, s21, s9
	global_load_dwordx4 v[10:13], v234, s[8:9]
	global_load_dwordx4 v[14:17], v233, s[8:9]
	ds_read_b128 v[186:189], v247 offset:12288
	v_mfma_f32_16x16x32_bf16 v[46:49], v[194:197], v[190:193], v[46:49]
	v_mfma_f32_16x16x32_bf16 v[38:41], v[198:201], v[190:193], v[38:41]
	v_mfma_f32_16x16x32_bf16 v[42:45], v[202:205], v[190:193], v[42:45]
	v_mfma_f32_16x16x32_bf16 v[34:37], v[206:209], v[190:193], v[34:37]
	ds_read_b128 v[190:193], v245 offset:12288
	s_waitcnt lgkmcnt(8)
	v_mfma_f32_16x16x32_bf16 v[158:161], v[210:213], v[162:165], v[158:161]
	v_mfma_f32_16x16x32_bf16 v[150:153], v[214:217], v[162:165], v[150:153]
	v_mfma_f32_16x16x32_bf16 v[154:157], v[218:221], v[162:165], v[154:157]
	v_mfma_f32_16x16x32_bf16 v[146:149], v[222:225], v[162:165], v[146:149]
	v_mfma_f32_16x16x32_bf16 v[142:145], v[210:213], v[166:169], v[142:145]
	v_mfma_f32_16x16x32_bf16 v[134:137], v[214:217], v[166:169], v[134:137]
	v_mfma_f32_16x16x32_bf16 v[138:141], v[218:221], v[166:169], v[138:141]
	v_mfma_f32_16x16x32_bf16 v[130:133], v[222:225], v[166:169], v[130:133]
	s_waitcnt vmcnt(6)
	ds_write_b128 v235, v[6:9] offset:49152
	ds_write_b128 v235, v[2:5] offset:57344

.LBB0_1164:
	s_waitcnt lgkmcnt(0)
	s_barrier
	ds_read_b128 v[194:197], v250
	ds_read_b128 v[198:201], v248
	ds_read_b128 v[202:205], v250 offset:4096
	ds_read_b128 v[206:209], v248 offset:4096
	ds_read_b128 v[162:165], v254
	ds_read_b128 v[166:169], v252
	ds_read_b128 v[170:173], v254 offset:4096
	ds_read_b128 v[174:177], v252 offset:4096
	v_mfma_f32_16x16x32_bf16 v[98:101], v[210:213], v[178:181], v[98:101]
	v_mfma_f32_16x16x32_bf16 v[90:93], v[214:217], v[178:181], v[90:93]
	v_mfma_f32_16x16x32_bf16 v[94:97], v[218:221], v[178:181], v[94:97]
	v_mfma_f32_16x16x32_bf16 v[86:89], v[222:225], v[178:181], v[86:89]
	v_mfma_f32_16x16x32_bf16 v[82:85], v[210:213], v[182:185], v[82:85]
	v_mfma_f32_16x16x32_bf16 v[74:77], v[214:217], v[182:185], v[74:77]
	v_mfma_f32_16x16x32_bf16 v[78:81], v[218:221], v[182:185], v[78:81]
	v_mfma_f32_16x16x32_bf16 v[70:73], v[222:225], v[182:185], v[70:73]
	v_mfma_f32_16x16x32_bf16 v[62:65], v[210:213], v[186:189], v[62:65]
	v_mfma_f32_16x16x32_bf16 v[54:57], v[214:217], v[186:189], v[54:57]
	v_mfma_f32_16x16x32_bf16 v[58:61], v[218:221], v[186:189], v[58:61]
	v_mfma_f32_16x16x32_bf16 v[50:53], v[222:225], v[186:189], v[50:53]
	v_mfma_f32_16x16x32_bf16 v[46:49], v[210:213], v[190:193], v[46:49]
	v_mfma_f32_16x16x32_bf16 v[38:41], v[214:217], v[190:193], v[38:41]
	v_mfma_f32_16x16x32_bf16 v[42:45], v[218:221], v[190:193], v[42:45]
	v_mfma_f32_16x16x32_bf16 v[34:37], v[222:225], v[190:193], v[34:37]
	ds_read_b128 v[186:189], v254 offset:12288
	ds_read_b128 v[182:185], v252 offset:8192
	ds_read_b128 v[178:181], v254 offset:8192
	ds_read_b128 v[190:193], v252 offset:12288
	s_cmp_lt_i32 s41, s40
	s_cselect_b64 s[20:21], -1, 0
	s_cmp_ge_i32 s41, s40
	s_cselect_b64 s[8:9], -1, 0
	s_waitcnt lgkmcnt(4)
	v_mfma_f32_16x16x32_bf16 v[158:161], v[194:197], v[162:165], v[158:161]
	v_mfma_f32_16x16x32_bf16 v[150:153], v[198:201], v[162:165], v[150:153]
	v_mfma_f32_16x16x32_bf16 v[154:157], v[202:205], v[162:165], v[154:157]
	v_mfma_f32_16x16x32_bf16 v[146:149], v[206:209], v[162:165], v[146:149]
	ds_read_b128 v[162:165], v246
	s_waitcnt lgkmcnt(2)
	v_mfma_f32_16x16x32_bf16 v[142:145], v[194:197], v[166:169], v[142:145]
	v_mfma_f32_16x16x32_bf16 v[134:137], v[198:201], v[166:169], v[134:137]
	v_mfma_f32_16x16x32_bf16 v[138:141], v[202:205], v[166:169], v[138:141]
	v_mfma_f32_16x16x32_bf16 v[130:133], v[206:209], v[166:169], v[130:133]
	s_waitcnt vmcnt(6)
	ds_write_b128 v236, v[26:29]
	ds_write_b128 v236, v[30:33] offset:8192
.LBB0_1166:
	s_lshl_b32 s2, s50, 6
	s_ashr_i32 s3, s2, 31
	s_add_u32 s22, s11, s12
	s_addc_u32 s23, s24, s13
	s_lshl_b64 s[12:13], s[2:3], 1
	s_add_u32 s22, s22, s12
	s_addc_u32 s23, s23, s13
	global_load_dwordx4 v[30:33], v234, s[22:23]
	global_load_dwordx4 v[26:29], v233, s[22:23]
	ds_read_b128 v[166:169], v244
	v_mfma_f32_16x16x32_bf16 v[126:129], v[194:197], v[170:173], v[126:129]
	v_mfma_f32_16x16x32_bf16 v[118:121], v[198:201], v[170:173], v[118:121]
	v_mfma_f32_16x16x32_bf16 v[122:125], v[202:205], v[170:173], v[122:125]
	v_mfma_f32_16x16x32_bf16 v[114:117], v[206:209], v[170:173], v[114:117]
	ds_read_b128 v[170:173], v246 offset:4096
	v_mfma_f32_16x16x32_bf16 v[110:113], v[194:197], v[174:177], v[110:113]
	v_mfma_f32_16x16x32_bf16 v[102:105], v[198:201], v[174:177], v[102:105]
	v_mfma_f32_16x16x32_bf16 v[106:109], v[202:205], v[174:177], v[106:109]
	v_mfma_f32_16x16x32_bf16 v[66:69], v[206:209], v[174:177], v[66:69]
	ds_read_b128 v[210:213], v242
	ds_read_b128 v[214:217], v237
	ds_read_b128 v[218:221], v242 offset:4096
	ds_read_b128 v[222:225], v237 offset:4096
	ds_read_b128 v[174:177], v244 offset:4096
	s_waitcnt lgkmcnt(10)
	v_mfma_f32_16x16x32_bf16 v[98:101], v[194:197], v[178:181], v[98:101]
	v_mfma_f32_16x16x32_bf16 v[90:93], v[198:201], v[178:181], v[90:93]
	v_mfma_f32_16x16x32_bf16 v[94:97], v[202:205], v[178:181], v[94:97]
	v_mfma_f32_16x16x32_bf16 v[86:89], v[206:209], v[178:181], v[86:89]
	s_waitcnt vmcnt(6)
	ds_write_b128 v236, v[18:21] offset:16384
	ds_write_b128 v236, v[22:25] offset:24576
.LBB0_1168:
	global_load_dwordx4 v[22:25], v232, s[22:23]
	global_load_dwordx4 v[18:21], v231, s[22:23]
	ds_read_b128 v[178:181], v246 offset:8192
	s_waitcnt lgkmcnt(4)
	v_mfma_f32_16x16x32_bf16 v[82:85], v[194:197], v[182:185], v[82:85]
	v_mfma_f32_16x16x32_bf16 v[74:77], v[198:201], v[182:185], v[74:77]
	v_mfma_f32_16x16x32_bf16 v[78:81], v[202:205], v[182:185], v[78:81]
	v_mfma_f32_16x16x32_bf16 v[70:73], v[206:209], v[182:185], v[70:73]
	ds_read_b128 v[182:185], v244 offset:8192
	v_mfma_f32_16x16x32_bf16 v[62:65], v[194:197], v[186:189], v[62:65]
	v_mfma_f32_16x16x32_bf16 v[54:57], v[198:201], v[186:189], v[54:57]
	v_mfma_f32_16x16x32_bf16 v[58:61], v[202:205], v[186:189], v[58:61]
	v_mfma_f32_16x16x32_bf16 v[50:53], v[206:209], v[186:189], v[50:53]
	s_waitcnt vmcnt(6)
	ds_write_b128 v236, v[10:13] offset:32768
	ds_write_b128 v236, v[14:17] offset:40960

.Lnodef_I0_3:
	ds_read_b128 v[114:117], v247 offset:4096
	ds_read_b128 v[118:121], v245 offset:4096
	s_waitcnt lgkmcnt(4)
	v_mfma_f32_16x16x32_bf16 v[58:61], v[122:125], v[90:93], v[58:61]
	v_mfma_f32_16x16x32_bf16 v[82:85], v[126:129], v[90:93], v[82:85]
	v_mfma_f32_16x16x32_bf16 v[86:89], v[130:133], v[90:93], v[86:89]
	v_mfma_f32_16x16x32_bf16 v[78:81], v[134:137], v[90:93], v[78:81]
	s_waitcnt lgkmcnt(3)
	v_mfma_f32_16x16x32_bf16 v[74:77], v[122:125], v[94:97], v[74:77]
	v_mfma_f32_16x16x32_bf16 v[66:69], v[126:129], v[94:97], v[66:69]
	v_mfma_f32_16x16x32_bf16 v[70:73], v[130:133], v[94:97], v[70:73]
	v_mfma_f32_16x16x32_bf16 v[62:65], v[134:137], v[94:97], v[62:65]
	s_waitcnt vmcnt(4)
	ds_write_b128 v238, v[22:25]
	ds_write_b128 v238, v[18:21] offset:8192
.LBB0_1205:
	s_lshl_b32 s2, s43, 8
	s_or_b32 s2, s2, s27
	s_ashr_i32 s3, s2, 31
	s_lshl_b64 s[12:13], s[2:3], 11
	s_lshl_b32 s2, s45, 6
	s_ashr_i32 s3, s2, 31
	s_add_u32 s14, s11, s12
	s_addc_u32 s15, s24, s13
	s_lshl_b64 s[20:21], s[2:3], 1
	s_add_u32 s2, s14, s20
	s_addc_u32 s3, s15, s21
	global_load_dwordx4 v[18:21], v237, s[2:3]
	global_load_dwordx4 v[22:25], v236, s[2:3]
	ds_read_b128 v[138:141], v243
	ds_read_b128 v[142:145], v241
	ds_read_b128 v[146:149], v243 offset:4096
	ds_read_b128 v[150:153], v241 offset:4096
	s_waitcnt lgkmcnt(0)
	v_mfma_f32_16x16x32_bf16 v[54:57], v[122:125], v[98:101], v[54:57]
	v_mfma_f32_16x16x32_bf16 v[46:49], v[126:129], v[98:101], v[46:49]
	v_mfma_f32_16x16x32_bf16 v[50:53], v[130:133], v[98:101], v[50:53]
	v_mfma_f32_16x16x32_bf16 v[42:45], v[134:137], v[98:101], v[42:45]
	s_waitcnt vmcnt(4)
	ds_write_b128 v238, v[14:17] offset:32768
	ds_write_b128 v238, v[10:13] offset:40960
.LBB0_1207:
	s_lshl_b32 s8, s42, 8
	s_ashr_i32 s9, s8, 31
	s_lshl_b64 s[14:15], s[8:9], 11
	s_add_u32 s8, s25, s14
	s_addc_u32 s9, s26, s15
	s_add_u32 s8, s8, s20
	s_addc_u32 s9, s9, s21
	global_load_dwordx4 v[10:13], v237, s[8:9]
	global_load_dwordx4 v[14:17], v236, s[8:9]
	v_mfma_f32_16x16x32_bf16 v[34:37], v[122:125], v[102:105], v[34:37]
	v_mfma_f32_16x16x32_bf16 v[30:33], v[126:129], v[102:105], v[30:33]
	v_mfma_f32_16x16x32_bf16 v[38:41], v[130:133], v[102:105], v[38:41]
	v_mfma_f32_16x16x32_bf16 v[26:29], v[134:137], v[102:105], v[26:29]
	s_waitcnt vmcnt(4)
	ds_write_b128 v238, v[6:9] offset:49152
	ds_write_b128 v238, v[2:5] offset:57344

.LBB0_1218:
	s_waitcnt lgkmcnt(0)
	s_barrier
	ds_read_b128 v[122:125], v250
	ds_read_b128 v[126:129], v248
	ds_read_b128 v[130:133], v250 offset:4096
	ds_read_b128 v[134:137], v248 offset:4096
	ds_read_b128 v[90:93], v254
	ds_read_b128 v[94:97], v252
	ds_read_b128 v[98:101], v254 offset:4096
	ds_read_b128 v[102:105], v252 offset:4096
	ds_read_b128 v[106:109], v246
	ds_read_b128 v[110:113], v244
	v_mfma_f32_16x16x32_bf16 v[54:57], v[138:141], v[114:117], v[54:57]
	v_mfma_f32_16x16x32_bf16 v[46:49], v[142:145], v[114:117], v[46:49]
	v_mfma_f32_16x16x32_bf16 v[50:53], v[146:149], v[114:117], v[50:53]
	v_mfma_f32_16x16x32_bf16 v[42:45], v[150:153], v[114:117], v[42:45]
	v_mfma_f32_16x16x32_bf16 v[34:37], v[138:141], v[118:121], v[34:37]
	v_mfma_f32_16x16x32_bf16 v[30:33], v[142:145], v[118:121], v[30:33]
	v_mfma_f32_16x16x32_bf16 v[38:41], v[146:149], v[118:121], v[38:41]
	v_mfma_f32_16x16x32_bf16 v[26:29], v[150:153], v[118:121], v[26:29]
	ds_read_b128 v[114:117], v246 offset:4096
	ds_read_b128 v[118:121], v244 offset:4096
	s_cmp_lt_i32 s36, s35
	s_cselect_b64 s[20:21], -1, 0
	s_cmp_ge_i32 s36, s35
	s_cselect_b64 s[8:9], -1, 0
	s_waitcnt lgkmcnt(4)
	v_mfma_f32_16x16x32_bf16 v[58:61], v[122:125], v[90:93], v[58:61]
	v_mfma_f32_16x16x32_bf16 v[82:85], v[126:129], v[90:93], v[82:85]
	v_mfma_f32_16x16x32_bf16 v[86:89], v[130:133], v[90:93], v[86:89]
	v_mfma_f32_16x16x32_bf16 v[78:81], v[134:137], v[90:93], v[78:81]
	s_waitcnt lgkmcnt(3)
	v_mfma_f32_16x16x32_bf16 v[74:77], v[122:125], v[94:97], v[74:77]
	v_mfma_f32_16x16x32_bf16 v[66:69], v[126:129], v[94:97], v[66:69]
	v_mfma_f32_16x16x32_bf16 v[70:73], v[130:133], v[94:97], v[70:73]
	v_mfma_f32_16x16x32_bf16 v[62:65], v[134:137], v[94:97], v[62:65]
	s_waitcnt vmcnt(4)
	ds_write_b128 v239, v[18:21]
	ds_write_b128 v239, v[22:25] offset:8192
.LBB0_1220:
	s_lshl_b32 s2, s45, 6
	s_ashr_i32 s3, s2, 31
	s_add_u32 s46, s11, s12
	s_addc_u32 s47, s24, s13
	s_lshl_b64 s[12:13], s[2:3], 1
	s_add_u32 s2, s46, s12
	s_addc_u32 s3, s47, s13
	global_load_dwordx4 v[22:25], v237, s[2:3]
	global_load_dwordx4 v[18:21], v236, s[2:3]
	ds_read_b128 v[138:141], v242
	ds_read_b128 v[142:145], v240
	ds_read_b128 v[146:149], v242 offset:4096
	ds_read_b128 v[150:153], v240 offset:4096
	s_waitcnt lgkmcnt(0)
	v_mfma_f32_16x16x32_bf16 v[54:57], v[122:125], v[98:101], v[54:57]
	v_mfma_f32_16x16x32_bf16 v[46:49], v[126:129], v[98:101], v[46:49]
	v_mfma_f32_16x16x32_bf16 v[50:53], v[130:133], v[98:101], v[50:53]
	v_mfma_f32_16x16x32_bf16 v[42:45], v[134:137], v[98:101], v[42:45]
	s_waitcnt vmcnt(4)
	ds_write_b128 v239, v[10:13] offset:32768
	ds_write_b128 v239, v[14:17] offset:40960

.LBB0_1304:
	s_lshl_b32 s2, s49, 8
	s_mul_i32 s20, s49, 0xb0000
	s_mul_hi_i32 s21, s2, 0xb00
	s_lshl_b32 s2, s26, 6
	s_ashr_i32 s3, s2, 31
	s_lshl_b64 s[6:7], s[20:21], 1
	s_add_u32 s24, s29, s6
	s_addc_u32 s25, s30, s7
	s_lshl_b64 s[6:7], s[2:3], 1
	s_add_u32 s24, s24, s6
	s_addc_u32 s25, s25, s7
	global_load_dwordx4 v[26:29], v234, s[24:25]
	global_load_dwordx4 v[30:33], v233, s[24:25]
	ds_read_b128 v[166:169], v245
	v_mfma_f32_16x16x32_bf16 v[126:129], v[194:197], v[170:173], v[126:129]
	v_mfma_f32_16x16x32_bf16 v[122:125], v[198:201], v[170:173], v[122:125]
	v_mfma_f32_16x16x32_bf16 v[118:121], v[202:205], v[170:173], v[118:121]
	v_mfma_f32_16x16x32_bf16 v[114:117], v[206:209], v[170:173], v[114:117]
	ds_read_b128 v[170:173], v247 offset:4096
	v_mfma_f32_16x16x32_bf16 v[110:113], v[194:197], v[174:177], v[110:113]
	v_mfma_f32_16x16x32_bf16 v[106:109], v[198:201], v[174:177], v[106:109]
	v_mfma_f32_16x16x32_bf16 v[102:105], v[202:205], v[174:177], v[102:105]
	v_mfma_f32_16x16x32_bf16 v[82:85], v[206:209], v[174:177], v[82:85]
	ds_read_b128 v[210:213], v243
	ds_read_b128 v[214:217], v241
	ds_read_b128 v[218:221], v243 offset:4096
	ds_read_b128 v[222:225], v241 offset:4096
	ds_read_b128 v[174:177], v245 offset:4096
	s_waitcnt lgkmcnt(10)
	v_mfma_f32_16x16x32_bf16 v[98:101], v[194:197], v[178:181], v[98:101]
	v_mfma_f32_16x16x32_bf16 v[94:97], v[198:201], v[178:181], v[94:97]
	v_mfma_f32_16x16x32_bf16 v[90:93], v[202:205], v[178:181], v[90:93]
	v_mfma_f32_16x16x32_bf16 v[86:89], v[206:209], v[178:181], v[86:89]
	s_waitcnt vmcnt(6)
	ds_write_b128 v235, v[22:25] offset:16384
	ds_write_b128 v235, v[18:21] offset:24576
.LBB0_1306:
	global_load_dwordx4 v[18:21], v232, s[24:25]
	global_load_dwordx4 v[22:25], v231, s[24:25]
	ds_read_b128 v[178:181], v247 offset:8192
	s_waitcnt lgkmcnt(4)
	v_mfma_f32_16x16x32_bf16 v[78:81], v[194:197], v[182:185], v[78:81]
	v_mfma_f32_16x16x32_bf16 v[74:77], v[198:201], v[182:185], v[74:77]
	v_mfma_f32_16x16x32_bf16 v[70:73], v[202:205], v[182:185], v[70:73]
	v_mfma_f32_16x16x32_bf16 v[66:69], v[206:209], v[182:185], v[66:69]
	ds_read_b128 v[182:185], v245 offset:8192
	v_mfma_f32_16x16x32_bf16 v[62:65], v[194:197], v[186:189], v[62:65]
	v_mfma_f32_16x16x32_bf16 v[58:61], v[198:201], v[186:189], v[58:61]
	v_mfma_f32_16x16x32_bf16 v[54:57], v[202:205], v[186:189], v[54:57]
	v_mfma_f32_16x16x32_bf16 v[50:53], v[206:209], v[186:189], v[50:53]
	s_waitcnt vmcnt(6)
	ds_write_b128 v235, v[14:17] offset:32768
	ds_write_b128 v235, v[10:13] offset:40960
.LBB0_1308:
	s_lshl_b32 s23, s48, 8
	s_mul_i32 s22, s48, 0xb0000
	s_mul_hi_i32 s23, s23, 0xb00
	s_lshl_b64 s[24:25], s[22:23], 1
	s_add_u32 s24, s31, s24
	s_addc_u32 s25, s33, s25
	s_add_u32 s6, s24, s6
	s_addc_u32 s7, s25, s7
	global_load_dwordx4 v[10:13], v234, s[6:7]
	global_load_dwordx4 v[14:17], v233, s[6:7]
	ds_read_b128 v[186:189], v247 offset:12288
	v_mfma_f32_16x16x32_bf16 v[46:49], v[194:197], v[190:193], v[46:49]
	v_mfma_f32_16x16x32_bf16 v[42:45], v[198:201], v[190:193], v[42:45]
	v_mfma_f32_16x16x32_bf16 v[38:41], v[202:205], v[190:193], v[38:41]
	v_mfma_f32_16x16x32_bf16 v[34:37], v[206:209], v[190:193], v[34:37]
	ds_read_b128 v[190:193], v245 offset:12288
	s_waitcnt lgkmcnt(8)
	v_mfma_f32_16x16x32_bf16 v[158:161], v[210:213], v[162:165], v[158:161]
	v_mfma_f32_16x16x32_bf16 v[154:157], v[214:217], v[162:165], v[154:157]
	v_mfma_f32_16x16x32_bf16 v[150:153], v[218:221], v[162:165], v[150:153]
	v_mfma_f32_16x16x32_bf16 v[146:149], v[222:225], v[162:165], v[146:149]
	v_mfma_f32_16x16x32_bf16 v[142:145], v[210:213], v[166:169], v[142:145]
	v_mfma_f32_16x16x32_bf16 v[138:141], v[214:217], v[166:169], v[138:141]
	v_mfma_f32_16x16x32_bf16 v[134:137], v[218:221], v[166:169], v[134:137]
	v_mfma_f32_16x16x32_bf16 v[130:133], v[222:225], v[166:169], v[130:133]
	s_waitcnt vmcnt(6)
	ds_write_b128 v235, v[6:9] offset:49152
	ds_write_b128 v235, v[2:5] offset:57344

.LBB0_1314:
	s_waitcnt lgkmcnt(0)
	s_barrier
	ds_read_b128 v[194:197], v250
	ds_read_b128 v[198:201], v248
	ds_read_b128 v[202:205], v250 offset:4096
	ds_read_b128 v[206:209], v248 offset:4096
	ds_read_b128 v[162:165], v254
	ds_read_b128 v[166:169], v252
	ds_read_b128 v[170:173], v254 offset:4096
	ds_read_b128 v[174:177], v252 offset:4096
	v_mfma_f32_16x16x32_bf16 v[98:101], v[210:213], v[178:181], v[98:101]
	v_mfma_f32_16x16x32_bf16 v[94:97], v[214:217], v[178:181], v[94:97]
	v_mfma_f32_16x16x32_bf16 v[90:93], v[218:221], v[178:181], v[90:93]
	v_mfma_f32_16x16x32_bf16 v[86:89], v[222:225], v[178:181], v[86:89]
	v_mfma_f32_16x16x32_bf16 v[78:81], v[210:213], v[182:185], v[78:81]
	v_mfma_f32_16x16x32_bf16 v[74:77], v[214:217], v[182:185], v[74:77]
	v_mfma_f32_16x16x32_bf16 v[70:73], v[218:221], v[182:185], v[70:73]
	v_mfma_f32_16x16x32_bf16 v[66:69], v[222:225], v[182:185], v[66:69]
	v_mfma_f32_16x16x32_bf16 v[62:65], v[210:213], v[186:189], v[62:65]
	v_mfma_f32_16x16x32_bf16 v[58:61], v[214:217], v[186:189], v[58:61]
	v_mfma_f32_16x16x32_bf16 v[54:57], v[218:221], v[186:189], v[54:57]
	v_mfma_f32_16x16x32_bf16 v[50:53], v[222:225], v[186:189], v[50:53]
	v_mfma_f32_16x16x32_bf16 v[46:49], v[210:213], v[190:193], v[46:49]
	v_mfma_f32_16x16x32_bf16 v[42:45], v[214:217], v[190:193], v[42:45]
	v_mfma_f32_16x16x32_bf16 v[38:41], v[218:221], v[190:193], v[38:41]
	v_mfma_f32_16x16x32_bf16 v[34:37], v[222:225], v[190:193], v[34:37]
	ds_read_b128 v[186:189], v254 offset:12288
	ds_read_b128 v[182:185], v252 offset:8192
	ds_read_b128 v[178:181], v254 offset:8192
	ds_read_b128 v[190:193], v252 offset:12288
	s_cmp_lt_i32 s39, s41
	s_cselect_b64 s[24:25], -1, 0
	s_cmp_ge_i32 s39, s41
	s_cselect_b64 s[6:7], -1, 0
	s_waitcnt lgkmcnt(4)
	v_mfma_f32_16x16x32_bf16 v[158:161], v[194:197], v[162:165], v[158:161]
	v_mfma_f32_16x16x32_bf16 v[154:157], v[198:201], v[162:165], v[154:157]
	v_mfma_f32_16x16x32_bf16 v[150:153], v[202:205], v[162:165], v[150:153]
	v_mfma_f32_16x16x32_bf16 v[146:149], v[206:209], v[162:165], v[146:149]
	ds_read_b128 v[162:165], v246
	s_waitcnt lgkmcnt(2)
	v_mfma_f32_16x16x32_bf16 v[142:145], v[194:197], v[166:169], v[142:145]
	v_mfma_f32_16x16x32_bf16 v[138:141], v[198:201], v[166:169], v[138:141]
	v_mfma_f32_16x16x32_bf16 v[134:137], v[202:205], v[166:169], v[134:137]
	v_mfma_f32_16x16x32_bf16 v[130:133], v[206:209], v[166:169], v[130:133]
	s_waitcnt vmcnt(6)
	ds_write_b128 v236, v[26:29]
	ds_write_b128 v236, v[30:33] offset:8192
.LBB0_1316:
	s_lshl_b32 s2, s51, 6
	s_ashr_i32 s3, s2, 31
	s_lshl_b64 s[20:21], s[20:21], 1
	s_add_u32 s26, s29, s20
	s_addc_u32 s27, s30, s21
	s_lshl_b64 s[20:21], s[2:3], 1
	s_add_u32 s26, s26, s20
	s_addc_u32 s27, s27, s21
	global_load_dwordx4 v[30:33], v234, s[26:27]
	global_load_dwordx4 v[26:29], v233, s[26:27]
	ds_read_b128 v[166:169], v244
	v_mfma_f32_16x16x32_bf16 v[126:129], v[194:197], v[170:173], v[126:129]
	v_mfma_f32_16x16x32_bf16 v[122:125], v[198:201], v[170:173], v[122:125]
	v_mfma_f32_16x16x32_bf16 v[118:121], v[202:205], v[170:173], v[118:121]
	v_mfma_f32_16x16x32_bf16 v[114:117], v[206:209], v[170:173], v[114:117]
	ds_read_b128 v[170:173], v246 offset:4096
	v_mfma_f32_16x16x32_bf16 v[110:113], v[194:197], v[174:177], v[110:113]
	v_mfma_f32_16x16x32_bf16 v[106:109], v[198:201], v[174:177], v[106:109]
	v_mfma_f32_16x16x32_bf16 v[102:105], v[202:205], v[174:177], v[102:105]
	v_mfma_f32_16x16x32_bf16 v[82:85], v[206:209], v[174:177], v[82:85]
	ds_read_b128 v[210:213], v242
	ds_read_b128 v[214:217], v237
	ds_read_b128 v[218:221], v242 offset:4096
	ds_read_b128 v[222:225], v237 offset:4096
	ds_read_b128 v[174:177], v244 offset:4096
	s_waitcnt lgkmcnt(10)
	v_mfma_f32_16x16x32_bf16 v[98:101], v[194:197], v[178:181], v[98:101]
	v_mfma_f32_16x16x32_bf16 v[94:97], v[198:201], v[178:181], v[94:97]
	v_mfma_f32_16x16x32_bf16 v[90:93], v[202:205], v[178:181], v[90:93]
	v_mfma_f32_16x16x32_bf16 v[86:89], v[206:209], v[178:181], v[86:89]
	s_waitcnt vmcnt(6)
	ds_write_b128 v236, v[18:21] offset:16384
	ds_write_b128 v236, v[22:25] offset:24576
.LBB0_1318:
	global_load_dwordx4 v[22:25], v232, s[26:27]
	global_load_dwordx4 v[18:21], v231, s[26:27]
	ds_read_b128 v[178:181], v246 offset:8192
	s_waitcnt lgkmcnt(4)
	v_mfma_f32_16x16x32_bf16 v[78:81], v[194:197], v[182:185], v[78:81]
	v_mfma_f32_16x16x32_bf16 v[74:77], v[198:201], v[182:185], v[74:77]
	v_mfma_f32_16x16x32_bf16 v[70:73], v[202:205], v[182:185], v[70:73]
	v_mfma_f32_16x16x32_bf16 v[66:69], v[206:209], v[182:185], v[66:69]
	ds_read_b128 v[182:185], v244 offset:8192
	v_mfma_f32_16x16x32_bf16 v[62:65], v[194:197], v[186:189], v[62:65]
	v_mfma_f32_16x16x32_bf16 v[58:61], v[198:201], v[186:189], v[58:61]
	v_mfma_f32_16x16x32_bf16 v[54:57], v[202:205], v[186:189], v[54:57]
	v_mfma_f32_16x16x32_bf16 v[50:53], v[206:209], v[186:189], v[50:53]
	s_waitcnt vmcnt(6)
	ds_write_b128 v236, v[10:13] offset:32768
	ds_write_b128 v236, v[14:17] offset:40960

.LBB0_2205:
	s_lshl_b32 s6, s49, 8
	s_ashr_i32 s7, s6, 31
	s_lshl_b32 s2, s26, 6
	s_ashr_i32 s3, s2, 31
	s_lshl_b64 s[20:21], s[6:7], 11
	s_add_u32 s24, s29, s20
	s_addc_u32 s25, s30, s21
	s_lshl_b64 s[20:21], s[2:3], 1
	s_add_u32 s24, s24, s20
	s_addc_u32 s25, s25, s21
	global_load_dwordx4 v[30:33], v233, s[24:25]
	global_load_dwordx4 v[26:29], v234, s[24:25]
	ds_read_b128 v[166:169], v245
	v_mfma_f32_16x16x32_bf16 v[126:129], v[194:197], v[170:173], v[126:129]
	v_mfma_f32_16x16x32_bf16 v[122:125], v[198:201], v[170:173], v[122:125]
	v_mfma_f32_16x16x32_bf16 v[118:121], v[202:205], v[170:173], v[118:121]
	v_mfma_f32_16x16x32_bf16 v[114:117], v[206:209], v[170:173], v[114:117]
	ds_read_b128 v[170:173], v247 offset:4096
	v_mfma_f32_16x16x32_bf16 v[110:113], v[194:197], v[174:177], v[110:113]
	v_mfma_f32_16x16x32_bf16 v[106:109], v[198:201], v[174:177], v[106:109]
	v_mfma_f32_16x16x32_bf16 v[102:105], v[202:205], v[174:177], v[102:105]
	v_mfma_f32_16x16x32_bf16 v[82:85], v[206:209], v[174:177], v[82:85]
	ds_read_b128 v[210:213], v243
	ds_read_b128 v[214:217], v241
	ds_read_b128 v[218:221], v243 offset:4096
	ds_read_b128 v[222:225], v241 offset:4096
	ds_read_b128 v[174:177], v245 offset:4096
	s_waitcnt lgkmcnt(10)
	v_mfma_f32_16x16x32_bf16 v[98:101], v[194:197], v[178:181], v[98:101]
	v_mfma_f32_16x16x32_bf16 v[94:97], v[198:201], v[178:181], v[94:97]
	v_mfma_f32_16x16x32_bf16 v[90:93], v[202:205], v[178:181], v[90:93]
	v_mfma_f32_16x16x32_bf16 v[86:89], v[206:209], v[178:181], v[86:89]
	s_waitcnt vmcnt(6)
	ds_write_b128 v235, v[22:25] offset:16384
	ds_write_b128 v235, v[18:21] offset:24576

.LBB0_2209:
	s_lshl_b32 s22, s48, 8
	s_ashr_i32 s23, s22, 31
	s_lshl_b64 s[24:25], s[22:23], 11
	s_add_u32 s24, s31, s24
	s_addc_u32 s25, s33, s25
	s_add_u32 s20, s24, s20
	s_addc_u32 s21, s25, s21
	global_load_dwordx4 v[10:13], v234, s[20:21]
	global_load_dwordx4 v[14:17], v233, s[20:21]
	ds_read_b128 v[186:189], v247 offset:12288
	v_mfma_f32_16x16x32_bf16 v[46:49], v[194:197], v[190:193], v[46:49]
	v_mfma_f32_16x16x32_bf16 v[42:45], v[198:201], v[190:193], v[42:45]
	v_mfma_f32_16x16x32_bf16 v[38:41], v[202:205], v[190:193], v[38:41]
	v_mfma_f32_16x16x32_bf16 v[34:37], v[206:209], v[190:193], v[34:37]
	ds_read_b128 v[190:193], v245 offset:12288
	s_waitcnt lgkmcnt(8)
	v_mfma_f32_16x16x32_bf16 v[158:161], v[210:213], v[162:165], v[158:161]
	v_mfma_f32_16x16x32_bf16 v[154:157], v[214:217], v[162:165], v[154:157]
	v_mfma_f32_16x16x32_bf16 v[150:153], v[218:221], v[162:165], v[150:153]
	v_mfma_f32_16x16x32_bf16 v[146:149], v[222:225], v[162:165], v[146:149]
	v_mfma_f32_16x16x32_bf16 v[142:145], v[210:213], v[166:169], v[142:145]
	v_mfma_f32_16x16x32_bf16 v[138:141], v[214:217], v[166:169], v[138:141]
	v_mfma_f32_16x16x32_bf16 v[134:137], v[218:221], v[166:169], v[134:137]
	v_mfma_f32_16x16x32_bf16 v[130:133], v[222:225], v[166:169], v[130:133]
	s_waitcnt vmcnt(6)
	ds_write_b128 v235, v[6:9] offset:49152
	ds_write_b128 v235, v[2:5] offset:57344

.LBB0_2215:
	s_waitcnt lgkmcnt(0)
	s_barrier
	ds_read_b128 v[194:197], v250
	ds_read_b128 v[198:201], v248
	ds_read_b128 v[202:205], v250 offset:4096
	ds_read_b128 v[206:209], v248 offset:4096
	ds_read_b128 v[162:165], v254
	ds_read_b128 v[166:169], v252
	ds_read_b128 v[170:173], v254 offset:4096
	ds_read_b128 v[174:177], v252 offset:4096
	v_mfma_f32_16x16x32_bf16 v[98:101], v[210:213], v[178:181], v[98:101]
	v_mfma_f32_16x16x32_bf16 v[94:97], v[214:217], v[178:181], v[94:97]
	v_mfma_f32_16x16x32_bf16 v[90:93], v[218:221], v[178:181], v[90:93]
	v_mfma_f32_16x16x32_bf16 v[86:89], v[222:225], v[178:181], v[86:89]
	v_mfma_f32_16x16x32_bf16 v[78:81], v[210:213], v[182:185], v[78:81]
	v_mfma_f32_16x16x32_bf16 v[74:77], v[214:217], v[182:185], v[74:77]
	v_mfma_f32_16x16x32_bf16 v[70:73], v[218:221], v[182:185], v[70:73]
	v_mfma_f32_16x16x32_bf16 v[66:69], v[222:225], v[182:185], v[66:69]
	v_mfma_f32_16x16x32_bf16 v[62:65], v[210:213], v[186:189], v[62:65]
	v_mfma_f32_16x16x32_bf16 v[58:61], v[214:217], v[186:189], v[58:61]
	v_mfma_f32_16x16x32_bf16 v[54:57], v[218:221], v[186:189], v[54:57]
	v_mfma_f32_16x16x32_bf16 v[50:53], v[222:225], v[186:189], v[50:53]
	v_mfma_f32_16x16x32_bf16 v[46:49], v[210:213], v[190:193], v[46:49]
	v_mfma_f32_16x16x32_bf16 v[42:45], v[214:217], v[190:193], v[42:45]
	v_mfma_f32_16x16x32_bf16 v[38:41], v[218:221], v[190:193], v[38:41]
	v_mfma_f32_16x16x32_bf16 v[34:37], v[222:225], v[190:193], v[34:37]
	ds_read_b128 v[186:189], v254 offset:12288
	ds_read_b128 v[182:185], v252 offset:8192
	ds_read_b128 v[178:181], v254 offset:8192
	ds_read_b128 v[190:193], v252 offset:12288
	s_cmp_lt_i32 s40, s35
	s_cselect_b64 s[24:25], -1, 0
	s_cmp_ge_i32 s40, s35
	s_cselect_b64 s[6:7], -1, 0
	s_waitcnt lgkmcnt(4)
	v_mfma_f32_16x16x32_bf16 v[158:161], v[194:197], v[162:165], v[158:161]
	v_mfma_f32_16x16x32_bf16 v[154:157], v[198:201], v[162:165], v[154:157]
	v_mfma_f32_16x16x32_bf16 v[150:153], v[202:205], v[162:165], v[150:153]
	v_mfma_f32_16x16x32_bf16 v[146:149], v[206:209], v[162:165], v[146:149]
	ds_read_b128 v[162:165], v246
	s_waitcnt lgkmcnt(2)
	v_mfma_f32_16x16x32_bf16 v[142:145], v[194:197], v[166:169], v[142:145]
	v_mfma_f32_16x16x32_bf16 v[138:141], v[198:201], v[166:169], v[138:141]
	v_mfma_f32_16x16x32_bf16 v[134:137], v[202:205], v[166:169], v[134:137]
	v_mfma_f32_16x16x32_bf16 v[130:133], v[206:209], v[166:169], v[130:133]
	s_waitcnt vmcnt(6)
	ds_write_b128 v236, v[26:29]
	ds_write_b128 v236, v[30:33] offset:8192
.LBB0_2217:
	s_lshl_b32 s22, s51, 6
	s_ashr_i32 s23, s22, 31
	s_lshl_b64 s[2:3], s[2:3], 1
	s_add_u32 s2, s29, s2
	s_addc_u32 s3, s30, s3
	s_lshl_b64 s[22:23], s[22:23], 1
	s_add_u32 s26, s2, s22
	s_addc_u32 s27, s3, s23
	global_load_dwordx4 v[30:33], v234, s[26:27]
	global_load_dwordx4 v[26:29], v233, s[26:27]
	ds_read_b128 v[166:169], v244
	v_mfma_f32_16x16x32_bf16 v[126:129], v[194:197], v[170:173], v[126:129]
	v_mfma_f32_16x16x32_bf16 v[122:125], v[198:201], v[170:173], v[122:125]
	v_mfma_f32_16x16x32_bf16 v[118:121], v[202:205], v[170:173], v[118:121]
	v_mfma_f32_16x16x32_bf16 v[114:117], v[206:209], v[170:173], v[114:117]
	ds_read_b128 v[170:173], v246 offset:4096
	v_mfma_f32_16x16x32_bf16 v[110:113], v[194:197], v[174:177], v[110:113]
	v_mfma_f32_16x16x32_bf16 v[106:109], v[198:201], v[174:177], v[106:109]
	v_mfma_f32_16x16x32_bf16 v[102:105], v[202:205], v[174:177], v[102:105]
	v_mfma_f32_16x16x32_bf16 v[82:85], v[206:209], v[174:177], v[82:85]
	ds_read_b128 v[210:213], v242
	ds_read_b128 v[214:217], v237
	ds_read_b128 v[218:221], v242 offset:4096
	ds_read_b128 v[222:225], v237 offset:4096
	ds_read_b128 v[174:177], v244 offset:4096
	s_waitcnt lgkmcnt(10)
	v_mfma_f32_16x16x32_bf16 v[98:101], v[194:197], v[178:181], v[98:101]
	v_mfma_f32_16x16x32_bf16 v[94:97], v[198:201], v[178:181], v[94:97]
	v_mfma_f32_16x16x32_bf16 v[90:93], v[202:205], v[178:181], v[90:93]
	v_mfma_f32_16x16x32_bf16 v[86:89], v[206:209], v[178:181], v[86:89]
	s_waitcnt vmcnt(6)
	ds_write_b128 v236, v[18:21] offset:16384
	ds_write_b128 v236, v[22:25] offset:24576

.LBB0_2547:
	s_lshl_b32 s0, s41, 8
	s_mul_i32 s12, s41, 0xb0000
	s_mul_hi_i32 s13, s0, 0xb00
	s_lshl_b32 s0, s18, 6
	s_ashr_i32 s1, s0, 31
	s_lshl_b64 s[6:7], s[12:13], 1
	s_add_u32 s16, s21, s6
	s_addc_u32 s17, s22, s7
	s_lshl_b64 s[6:7], s[0:1], 1
	s_add_u32 s16, s16, s6
	s_addc_u32 s17, s17, s7
	global_load_dwordx4 v[26:29], v234, s[16:17]
	global_load_dwordx4 v[30:33], v233, s[16:17]
	ds_read_b128 v[166:169], v245
	v_mfma_f32_16x16x32_bf16 v[126:129], v[194:197], v[170:173], v[126:129]
	v_mfma_f32_16x16x32_bf16 v[122:125], v[198:201], v[170:173], v[122:125]
	v_mfma_f32_16x16x32_bf16 v[118:121], v[202:205], v[170:173], v[118:121]
	v_mfma_f32_16x16x32_bf16 v[114:117], v[206:209], v[170:173], v[114:117]
	ds_read_b128 v[170:173], v247 offset:4096
	v_mfma_f32_16x16x32_bf16 v[110:113], v[194:197], v[174:177], v[110:113]
	v_mfma_f32_16x16x32_bf16 v[106:109], v[198:201], v[174:177], v[106:109]
	v_mfma_f32_16x16x32_bf16 v[102:105], v[202:205], v[174:177], v[102:105]
	v_mfma_f32_16x16x32_bf16 v[82:85], v[206:209], v[174:177], v[82:85]
	ds_read_b128 v[210:213], v243
	ds_read_b128 v[214:217], v241
	ds_read_b128 v[218:221], v243 offset:4096
	ds_read_b128 v[222:225], v241 offset:4096
	ds_read_b128 v[174:177], v245 offset:4096
	s_waitcnt lgkmcnt(10)
	v_mfma_f32_16x16x32_bf16 v[98:101], v[194:197], v[178:181], v[98:101]
	v_mfma_f32_16x16x32_bf16 v[94:97], v[198:201], v[178:181], v[94:97]
	v_mfma_f32_16x16x32_bf16 v[90:93], v[202:205], v[178:181], v[90:93]
	v_mfma_f32_16x16x32_bf16 v[86:89], v[206:209], v[178:181], v[86:89]
	s_waitcnt vmcnt(6)
	ds_write_b128 v235, v[22:25] offset:16384
	ds_write_b128 v235, v[18:21] offset:24576
.LBB0_2549:
	global_load_dwordx4 v[18:21], v232, s[16:17]
	global_load_dwordx4 v[22:25], v231, s[16:17]
	ds_read_b128 v[178:181], v247 offset:8192
	s_waitcnt lgkmcnt(4)
	v_mfma_f32_16x16x32_bf16 v[78:81], v[194:197], v[182:185], v[78:81]
	v_mfma_f32_16x16x32_bf16 v[74:77], v[198:201], v[182:185], v[74:77]
	v_mfma_f32_16x16x32_bf16 v[70:73], v[202:205], v[182:185], v[70:73]
	v_mfma_f32_16x16x32_bf16 v[66:69], v[206:209], v[182:185], v[66:69]
	ds_read_b128 v[182:185], v245 offset:8192
	v_mfma_f32_16x16x32_bf16 v[62:65], v[194:197], v[186:189], v[62:65]
	v_mfma_f32_16x16x32_bf16 v[58:61], v[198:201], v[186:189], v[58:61]
	v_mfma_f32_16x16x32_bf16 v[54:57], v[202:205], v[186:189], v[54:57]
	v_mfma_f32_16x16x32_bf16 v[50:53], v[206:209], v[186:189], v[50:53]
	s_waitcnt vmcnt(6)
	ds_write_b128 v235, v[14:17] offset:32768
	ds_write_b128 v235, v[10:13] offset:40960
.LBB0_2551:
	s_lshl_b32 s15, s40, 8
	s_mul_i32 s14, s40, 0xb0000
	s_mul_hi_i32 s15, s15, 0xb00
	s_lshl_b64 s[16:17], s[14:15], 1
	s_add_u32 s16, s23, s16
	s_addc_u32 s17, s24, s17
	s_add_u32 s6, s16, s6
	s_addc_u32 s7, s17, s7
	global_load_dwordx4 v[10:13], v234, s[6:7]
	global_load_dwordx4 v[14:17], v233, s[6:7]
	ds_read_b128 v[186:189], v247 offset:12288
	v_mfma_f32_16x16x32_bf16 v[46:49], v[194:197], v[190:193], v[46:49]
	v_mfma_f32_16x16x32_bf16 v[42:45], v[198:201], v[190:193], v[42:45]
	v_mfma_f32_16x16x32_bf16 v[38:41], v[202:205], v[190:193], v[38:41]
	v_mfma_f32_16x16x32_bf16 v[34:37], v[206:209], v[190:193], v[34:37]
	ds_read_b128 v[190:193], v245 offset:12288
	s_waitcnt lgkmcnt(8)
	v_mfma_f32_16x16x32_bf16 v[158:161], v[210:213], v[162:165], v[158:161]
	v_mfma_f32_16x16x32_bf16 v[154:157], v[214:217], v[162:165], v[154:157]
	v_mfma_f32_16x16x32_bf16 v[150:153], v[218:221], v[162:165], v[150:153]
	v_mfma_f32_16x16x32_bf16 v[146:149], v[222:225], v[162:165], v[146:149]
	v_mfma_f32_16x16x32_bf16 v[142:145], v[210:213], v[166:169], v[142:145]
	v_mfma_f32_16x16x32_bf16 v[138:141], v[214:217], v[166:169], v[138:141]
	v_mfma_f32_16x16x32_bf16 v[134:137], v[218:221], v[166:169], v[134:137]
	v_mfma_f32_16x16x32_bf16 v[130:133], v[222:225], v[166:169], v[130:133]
	s_waitcnt vmcnt(6)
	ds_write_b128 v235, v[6:9] offset:49152
	ds_write_b128 v235, v[2:5] offset:57344

.LBB0_2557:
	s_waitcnt lgkmcnt(0)
	s_barrier
	ds_read_b128 v[194:197], v250
	ds_read_b128 v[198:201], v248
	ds_read_b128 v[202:205], v250 offset:4096
	ds_read_b128 v[206:209], v248 offset:4096
	ds_read_b128 v[162:165], v254
	ds_read_b128 v[166:169], v252
	ds_read_b128 v[170:173], v254 offset:4096
	ds_read_b128 v[174:177], v252 offset:4096
	v_mfma_f32_16x16x32_bf16 v[98:101], v[210:213], v[178:181], v[98:101]
	v_mfma_f32_16x16x32_bf16 v[94:97], v[214:217], v[178:181], v[94:97]
	v_mfma_f32_16x16x32_bf16 v[90:93], v[218:221], v[178:181], v[90:93]
	v_mfma_f32_16x16x32_bf16 v[86:89], v[222:225], v[178:181], v[86:89]
	v_mfma_f32_16x16x32_bf16 v[78:81], v[210:213], v[182:185], v[78:81]
	v_mfma_f32_16x16x32_bf16 v[74:77], v[214:217], v[182:185], v[74:77]
	v_mfma_f32_16x16x32_bf16 v[70:73], v[218:221], v[182:185], v[70:73]
	v_mfma_f32_16x16x32_bf16 v[66:69], v[222:225], v[182:185], v[66:69]
	v_mfma_f32_16x16x32_bf16 v[62:65], v[210:213], v[186:189], v[62:65]
	v_mfma_f32_16x16x32_bf16 v[58:61], v[214:217], v[186:189], v[58:61]
	v_mfma_f32_16x16x32_bf16 v[54:57], v[218:221], v[186:189], v[54:57]
	v_mfma_f32_16x16x32_bf16 v[50:53], v[222:225], v[186:189], v[50:53]
	v_mfma_f32_16x16x32_bf16 v[46:49], v[210:213], v[190:193], v[46:49]
	v_mfma_f32_16x16x32_bf16 v[42:45], v[214:217], v[190:193], v[42:45]
	v_mfma_f32_16x16x32_bf16 v[38:41], v[218:221], v[190:193], v[38:41]
	v_mfma_f32_16x16x32_bf16 v[34:37], v[222:225], v[190:193], v[34:37]
	ds_read_b128 v[186:189], v254 offset:12288
	ds_read_b128 v[182:185], v252 offset:8192
	ds_read_b128 v[178:181], v254 offset:8192
	ds_read_b128 v[190:193], v252 offset:12288
	s_cmp_lt_i32 s30, s33
	s_cselect_b64 s[16:17], -1, 0
	s_cmp_ge_i32 s30, s33
	s_cselect_b64 s[6:7], -1, 0
	s_waitcnt lgkmcnt(4)
	v_mfma_f32_16x16x32_bf16 v[158:161], v[194:197], v[162:165], v[158:161]
	v_mfma_f32_16x16x32_bf16 v[154:157], v[198:201], v[162:165], v[154:157]
	v_mfma_f32_16x16x32_bf16 v[150:153], v[202:205], v[162:165], v[150:153]
	v_mfma_f32_16x16x32_bf16 v[146:149], v[206:209], v[162:165], v[146:149]
	ds_read_b128 v[162:165], v246
	s_waitcnt lgkmcnt(2)
	v_mfma_f32_16x16x32_bf16 v[142:145], v[194:197], v[166:169], v[142:145]
	v_mfma_f32_16x16x32_bf16 v[138:141], v[198:201], v[166:169], v[138:141]
	v_mfma_f32_16x16x32_bf16 v[134:137], v[202:205], v[166:169], v[134:137]
	v_mfma_f32_16x16x32_bf16 v[130:133], v[206:209], v[166:169], v[130:133]
	s_waitcnt vmcnt(6)
	ds_write_b128 v236, v[26:29]
	ds_write_b128 v236, v[30:33] offset:8192
.LBB0_2559:
	s_lshl_b32 s0, s43, 6
	s_ashr_i32 s1, s0, 31
	s_lshl_b64 s[12:13], s[12:13], 1
	s_add_u32 s18, s21, s12
	s_addc_u32 s19, s22, s13
	s_lshl_b64 s[12:13], s[0:1], 1
	s_add_u32 s18, s18, s12
	s_addc_u32 s19, s19, s13
	global_load_dwordx4 v[30:33], v234, s[18:19]
	global_load_dwordx4 v[26:29], v233, s[18:19]
	ds_read_b128 v[166:169], v244
	v_mfma_f32_16x16x32_bf16 v[126:129], v[194:197], v[170:173], v[126:129]
	v_mfma_f32_16x16x32_bf16 v[122:125], v[198:201], v[170:173], v[122:125]
	v_mfma_f32_16x16x32_bf16 v[118:121], v[202:205], v[170:173], v[118:121]
	v_mfma_f32_16x16x32_bf16 v[114:117], v[206:209], v[170:173], v[114:117]
	ds_read_b128 v[170:173], v246 offset:4096
	v_mfma_f32_16x16x32_bf16 v[110:113], v[194:197], v[174:177], v[110:113]
	v_mfma_f32_16x16x32_bf16 v[106:109], v[198:201], v[174:177], v[106:109]
	v_mfma_f32_16x16x32_bf16 v[102:105], v[202:205], v[174:177], v[102:105]
	v_mfma_f32_16x16x32_bf16 v[82:85], v[206:209], v[174:177], v[82:85]
	ds_read_b128 v[210:213], v242
	ds_read_b128 v[214:217], v237
	ds_read_b128 v[218:221], v242 offset:4096
	ds_read_b128 v[222:225], v237 offset:4096
	ds_read_b128 v[174:177], v244 offset:4096
	s_waitcnt lgkmcnt(10)
	v_mfma_f32_16x16x32_bf16 v[98:101], v[194:197], v[178:181], v[98:101]
	v_mfma_f32_16x16x32_bf16 v[94:97], v[198:201], v[178:181], v[94:97]
	v_mfma_f32_16x16x32_bf16 v[90:93], v[202:205], v[178:181], v[90:93]
	v_mfma_f32_16x16x32_bf16 v[86:89], v[206:209], v[178:181], v[86:89]
	s_waitcnt vmcnt(6)
	ds_write_b128 v236, v[18:21] offset:16384
	ds_write_b128 v236, v[22:25] offset:24576
.LBB0_2561:
	global_load_dwordx4 v[22:25], v232, s[18:19]
	global_load_dwordx4 v[18:21], v231, s[18:19]
	ds_read_b128 v[178:181], v246 offset:8192
	s_waitcnt lgkmcnt(4)
	v_mfma_f32_16x16x32_bf16 v[78:81], v[194:197], v[182:185], v[78:81]
	v_mfma_f32_16x16x32_bf16 v[74:77], v[198:201], v[182:185], v[74:77]
	v_mfma_f32_16x16x32_bf16 v[70:73], v[202:205], v[182:185], v[70:73]
	v_mfma_f32_16x16x32_bf16 v[66:69], v[206:209], v[182:185], v[66:69]
	ds_read_b128 v[182:185], v244 offset:8192
	v_mfma_f32_16x16x32_bf16 v[62:65], v[194:197], v[186:189], v[62:65]
	v_mfma_f32_16x16x32_bf16 v[58:61], v[198:201], v[186:189], v[58:61]
	v_mfma_f32_16x16x32_bf16 v[54:57], v[202:205], v[186:189], v[54:57]
	v_mfma_f32_16x16x32_bf16 v[50:53], v[206:209], v[186:189], v[50:53]
	s_waitcnt vmcnt(6)
	ds_write_b128 v236, v[10:13] offset:32768
	ds_write_b128 v236, v[14:17] offset:40960
